# v16 plus counted lgkmcnt waits in the two peeled post-loop PV blocks of the attention phase
# baseline (speedup 1.0000x reference)
; #define SBAR() __builtin_amdgcn_sched_barrier(0)
; __device__ __forceinline__ void finishSM(f32x16& p0, f32x16& p1, float alpha, float& l_reg, bf16x8& pa0, bf16x8& pa1, bf16x8& pa2, bf16x8& pa3) {
; #pragma unroll
;     for (int r = 0; r < 16; ++r) p1[r] = __builtin_amdgcn_exp2f(p1[r]);
;     float ps = 0;
; #pragma unroll
;     for (int r = 0; r < 16; ++r) ps += p0[r];
; #pragma unroll
;     for (int r = 0; r < 16; ++r) ps += p1[r];
;     { auto rr = __builtin_amdgcn_permlane32_swap(__float_as_uint(ps), __float_as_uint(ps), false, false);
;       ps = __uint_as_float(rr[0]) + __uint_as_float(rr[1]); }
;     l_reg = l_reg * alpha + ps;
;     PK4(p0, 0, pa0); PK4(p0, 8, pa1); PK4(p1, 0, pa2); PK4(p1, 8, pa3);
; }
; template <int KB>
; __device__ __forceinline__ void qkt(f32x16& p0, f32x16& p1, const char* K_lds, int r32, int hi, const bf16x8* qr, const char* qx) {
;     p0 = f32x16{}; p1 = f32x16{};
;     const char* kb[4];
; #pragma unroll
;     for (int dd = 0; dd < 4; ++dd) kb[dd] = K_lds + KB * SHM_K + KSWZ(r32, (dd * 16 + hi * 8) * 2);
; #pragma unroll
;     for (int d0 = 0; d0 < 12; ++d0) { const char* a = kb[d0 & 3] + (d0 >> 2) * 128;
;         bf16x8 b0 = *reinterpret_cast<const bf16x8*>(a);
;         bf16x8 b1 = *reinterpret_cast<const bf16x8*>(a + 32 * 384);
;         const bf16x8 q = d0 < 8 ? qr[d0 & 7] : *reinterpret_cast<const bf16x8*>(qx + (d0 - 8) * 1024);
;         p0 = __builtin_amdgcn_mfma_f32_32x32x16_bf16(b0, q, p0, 0, 0, 0);
;         p1 = __builtin_amdgcn_mfma_f32_32x32x16_bf16(b1, q, p1, 0, 0, 0); }
; }
; template <int VB>
; __device__ __forceinline__ void pv_tile(f32x16* o, int vb0, bf16x8 pa0, bf16x8 pa1, bf16x8 pa2, bf16x8 pa3) {
;     ...
;     PV_D2(0, 1); PV_D2(2, 3);
; __device__ __forceinline__ void attn_block(const BlockRef& cur, const BlockRef& nxt, char* lds, Seam& S) {
;     ...
;     SBAR(); qkt<1>(pB0, pB1, K_lds, r32, hi, S.qr, qx); SBAR();
;     finishSM(pA0, pA1, alA, l_reg, pa0, pa1, pa2, pa3); SBAR();
;     pv_tile<0>(o, vb0, pa0, pa1, pa2, pa3);
.LBB0_991:
	s_setprio 0
	v_readlane_b32 s68, v254, 55
	ds_read_b128 v[64:67], v194 offset:24576
	ds_read_b128 v[176:179], v194 offset:37120
	s_waitcnt lgkmcnt(1)
	v_mfma_f32_32x32x16_bf16 v[80:95], v[64:67], v[124:127], 0
	ds_read_b128 v[64:67], v194 offset:36864
	ds_read_b128 v[206:209], v194 offset:36992
	s_waitcnt lgkmcnt(1)
	v_mfma_f32_32x32x16_bf16 v[64:79], v[64:67], v[124:127], 0
	ds_read_b128 v[124:127], v195 offset:24576
	ds_read_b128 v[210:213], v195 offset:37120
	s_waitcnt lgkmcnt(1)
	v_mfma_f32_32x32x16_bf16 v[80:95], v[124:127], v[120:123], v[80:95]
	ds_read_b128 v[124:127], v195 offset:36864
	ds_read_b128 v[214:217], v195 offset:36992
	s_waitcnt lgkmcnt(1)
	v_mfma_f32_32x32x16_bf16 v[64:79], v[124:127], v[120:123], v[64:79]
	ds_read_b128 v[120:123], v196 offset:24576
	ds_read_b128 v[124:127], v196 offset:37120
	s_waitcnt lgkmcnt(1)
	v_mfma_f32_32x32x16_bf16 v[80:95], v[120:123], v[116:119], v[80:95]
	ds_read_b128 v[120:123], v196 offset:36864
	ds_read_b128 v[218:221], v196 offset:36992
	s_waitcnt lgkmcnt(1)
	v_mfma_f32_32x32x16_bf16 v[64:79], v[120:123], v[116:119], v[64:79]
	ds_read_b128 v[116:119], v197 offset:24576
	ds_read_b128 v[120:123], v197 offset:37120
	s_waitcnt lgkmcnt(1)
	v_mfma_f32_32x32x16_bf16 v[80:95], v[116:119], v[112:115], v[80:95]
	ds_read_b128 v[116:119], v197 offset:36864
	ds_read_b128 v[222:225], v197 offset:36992
	s_waitcnt lgkmcnt(1)
	v_mfma_f32_32x32x16_bf16 v[64:79], v[116:119], v[112:115], v[64:79]
	ds_read_b128 v[112:115], v194 offset:24704
	ds_read_b128 v[116:119], v194 offset:24832
	s_waitcnt lgkmcnt(1)
	v_mfma_f32_32x32x16_bf16 v[80:95], v[112:115], v[108:111], v[80:95]
	v_mfma_f32_32x32x16_bf16 v[64:79], v[206:209], v[108:111], v[64:79]
	ds_read_b128 v[108:111], v195 offset:24704
	ds_read_b128 v[112:115], v195 offset:24832
	s_waitcnt lgkmcnt(1)
	v_mfma_f32_32x32x16_bf16 v[80:95], v[108:111], v[104:107], v[80:95]
	v_mfma_f32_32x32x16_bf16 v[64:79], v[214:217], v[104:107], v[64:79]
	ds_read_b128 v[104:107], v196 offset:24704
	ds_read_b128 v[108:111], v196 offset:24832
	s_waitcnt lgkmcnt(1)
	v_mfma_f32_32x32x16_bf16 v[80:95], v[104:107], v[100:103], v[80:95]
	v_mfma_f32_32x32x16_bf16 v[64:79], v[218:221], v[100:103], v[64:79]
	ds_read_b128 v[100:103], v197 offset:24704
	ds_read_b128 v[104:107], v197 offset:24832
	s_waitcnt lgkmcnt(1)
	v_mfma_f32_32x32x16_bf16 v[80:95], v[100:103], v[96:99], v[80:95]
	v_mfma_f32_32x32x16_bf16 v[64:79], v[222:225], v[96:99], v[64:79]
	ds_read_b128 v[96:99], v204
	ds_read_b128 v[100:103], v204 offset:1024
	s_waitcnt lgkmcnt(1)
	v_mfma_f32_32x32x16_bf16 v[80:95], v[116:119], v[96:99], v[80:95]
	v_mfma_f32_32x32x16_bf16 v[64:79], v[176:179], v[96:99], v[64:79]
	s_waitcnt lgkmcnt(0)
	v_mfma_f32_32x32x16_bf16 v[80:95], v[112:115], v[100:103], v[80:95]
	v_mfma_f32_32x32x16_bf16 v[64:79], v[210:213], v[100:103], v[64:79]
	ds_read_b128 v[96:99], v204 offset:2048
	ds_read_b128 v[100:103], v204 offset:3072
	s_waitcnt lgkmcnt(1)
	v_mfma_f32_32x32x16_bf16 v[80:95], v[108:111], v[96:99], v[80:95]
	v_mfma_f32_32x32x16_bf16 v[64:79], v[124:127], v[96:99], v[64:79]
	s_waitcnt lgkmcnt(0)
	v_mfma_f32_32x32x16_bf16 v[80:95], v[104:107], v[100:103], v[80:95]
	v_mfma_f32_32x32x16_bf16 v[64:79], v[120:123], v[100:103], v[64:79]
	v_add_f32_e32 v96, 0, v159
	v_add_f32_e32 v96, v161, v96
	v_add_f32_e32 v96, v157, v96
	v_add_f32_e32 v96, v160, v96
	v_add_f32_e32 v96, v156, v96
	v_add_f32_e32 v96, v158, v96
	v_add_f32_e32 v96, v154, v96
	v_add_f32_e32 v96, v155, v96
	v_add_f32_e32 v96, v150, v96
	v_add_f32_e32 v96, v153, v96
	v_add_f32_e32 v96, v146, v96
	v_add_f32_e32 v96, v151, v96
	v_exp_f32_e32 v104, v142
	v_add_f32_e32 v96, v144, v96
	v_exp_f32_e32 v105, v143
	v_add_f32_e32 v96, v152, v96
	v_exp_f32_e32 v106, v140
	v_add_f32_e32 v96, v145, v96
	v_exp_f32_e32 v107, v141
	v_add_f32_e32 v96, v147, v96
	v_exp_f32_e32 v108, v138
	v_add_f32_e32 v96, v104, v96
	v_exp_f32_e32 v109, v139
	v_add_f32_e32 v96, v105, v96
	v_exp_f32_e32 v110, v136
	v_add_f32_e32 v96, v106, v96
	v_exp_f32_e32 v111, v137
	v_add_f32_e32 v96, v107, v96
	v_exp_f32_e32 v112, v134
	v_add_f32_e32 v96, v108, v96
	v_exp_f32_e32 v113, v135
	v_add_f32_e32 v96, v109, v96
	v_exp_f32_e32 v114, v132
	v_add_f32_e32 v96, v110, v96
	v_exp_f32_e32 v115, v133
	v_add_f32_e32 v96, v111, v96
	v_exp_f32_e32 v116, v130
	v_add_f32_e32 v96, v112, v96
	v_exp_f32_e32 v117, v131
	v_add_f32_e32 v96, v113, v96
	v_exp_f32_e32 v118, v128
	v_add_f32_e32 v96, v114, v96
	v_exp_f32_e32 v119, v129
	v_add_f32_e32 v96, v115, v96
	v_add_f32_e32 v96, v116, v96
	v_add_f32_e32 v96, v117, v96
	v_add_f32_e32 v96, v118, v96
	v_add_f32_e32 v162, v119, v96
	v_mov_b32_e32 v163, v162
	s_nop 1
	v_permlane32_swap_b32_e32 v162, v163
	v_cvt_pk_bf16_f32 v96, v159, v161
	v_cvt_pk_bf16_f32 v97, v157, v160
	v_cvt_pk_bf16_f32 v98, v156, v158
	v_cvt_pk_bf16_f32 v99, v154, v155
	v_cvt_pk_bf16_f32 v100, v150, v153
	v_cvt_pk_bf16_f32 v101, v146, v151
	v_cvt_pk_bf16_f32 v102, v144, v152
	v_cvt_pk_bf16_f32 v103, v145, v147
	v_cvt_pk_bf16_f32 v104, v104, v105
	v_cvt_pk_bf16_f32 v105, v106, v107
	v_cvt_pk_bf16_f32 v106, v108, v109
	v_cvt_pk_bf16_f32 v107, v110, v111
	v_cvt_pk_bf16_f32 v108, v112, v113
	v_cvt_pk_bf16_f32 v109, v114, v115
	v_cvt_pk_bf16_f32 v110, v116, v117
	v_cvt_pk_bf16_f32 v111, v118, v119
	s_nop 0
	v_permlane32_swap_b32_e32 v96, v98
	v_permlane32_swap_b32_e32 v97, v99
	v_permlane32_swap_b32_e32 v100, v102
	v_permlane32_swap_b32_e32 v101, v103
	v_permlane32_swap_b32_e32 v104, v106
	v_permlane32_swap_b32_e32 v105, v107
	v_permlane32_swap_b32_e32 v108, v110
	v_permlane32_swap_b32_e32 v109, v111
	ds_read_b64_tr_b16 v[112:113], v188 offset:0
	ds_read_b64_tr_b16 v[114:115], v188 offset:0x800
	ds_read_b64_tr_b16 v[116:117], v188 offset:0x200
	ds_read_b64_tr_b16 v[118:119], v188 offset:0xa00
	ds_read_b64_tr_b16 v[120:121], v188 offset:0x1000
	ds_read_b64_tr_b16 v[122:123], v188 offset:0x1800
	ds_read_b64_tr_b16 v[124:125], v188 offset:0x1200
	ds_read_b64_tr_b16 v[126:127], v188 offset:0x1a00
	ds_read_b64_tr_b16 v[128:129], v188 offset:0x2000
	ds_read_b64_tr_b16 v[130:131], v188 offset:0x2800
	ds_read_b64_tr_b16 v[132:133], v188 offset:0x2200
	ds_read_b64_tr_b16 v[134:135], v188 offset:0x2a00
	ds_read_b64_tr_b16 v[136:137], v188 offset:0x3000
	ds_read_b64_tr_b16 v[138:139], v188 offset:0x3800
	ds_read_b64_tr_b16 v[140:141], v188 offset:0x3200
	ds_read_b64_tr_b16 v[142:143], v188 offset:0x3a00
	s_waitcnt lgkmcnt(14)
; #define SBAR() __builtin_amdgcn_sched_barrier(0)
; #define RESC(a) do { if (__any((a) < 1.f)) { if (hi == 0) al_l[r32] = (a); asm volatile("s_waitcnt lgkmcnt(0)" ::: "memory");              \
;                      _Pragma("unroll") for (int d_ = 0; d_ < 4; ++d_) _Pragma("unroll") for (int r = 0; r < 16; ++r) o[d_][r] *= al_l[crow(r, hi)]; } } while (0)
; #define MASKT(P0_, P1_, t) do { const int kb_ = KBASE(t); if (kb_ + KVBLK - 1 > qlo) mask_tile(P0_, P1_, qm - kb_); } while (0)
; template <int VB>
; __device__ __forceinline__ void pv_tile(f32x16* o, int vb0, bf16x8 pa0, bf16x8 pa1, bf16x8 pa2, bf16x8 pa3) {
;     ...
;     PV_D2(0, 1); PV_D2(2, 3);
; __device__ __forceinline__ void attn_block(const BlockRef& cur, const BlockRef& nxt, char* lds, Seam& S) {
;     ...
;     SBAR(); SLOAD_H(nxt, 0); SBAR();
;     MASKT(pB0, pB1, NT - 1); partialSM(pB0, pB1, m_reg, mnB, alB); __syncthreads(); RESC(alB);
	s_nop 0
	v_mfma_f32_32x32x16_bf16 v[48:63], v[96:99], v[112:115], v[48:63]
	ds_read_b64_tr_b16 v[112:113], v188 offset:0x400
	ds_read_b64_tr_b16 v[114:115], v188 offset:0xc00
	s_waitcnt lgkmcnt(14)
	v_mfma_f32_32x32x16_bf16 v[32:47], v[96:99], v[116:119], v[32:47]
	ds_read_b64_tr_b16 v[116:117], v188 offset:0x600
	ds_read_b64_tr_b16 v[118:119], v188 offset:0xe00
	s_waitcnt lgkmcnt(14)
	v_mfma_f32_32x32x16_bf16 v[48:63], v[100:103], v[120:123], v[48:63]
	ds_read_b64_tr_b16 v[120:121], v188 offset:0x1400
	ds_read_b64_tr_b16 v[122:123], v188 offset:0x1c00
	s_waitcnt lgkmcnt(14)
	v_mfma_f32_32x32x16_bf16 v[32:47], v[100:103], v[124:127], v[32:47]
	ds_read_b64_tr_b16 v[124:125], v188 offset:0x1600
	ds_read_b64_tr_b16 v[126:127], v188 offset:0x1e00
	s_waitcnt lgkmcnt(14)
	v_mfma_f32_32x32x16_bf16 v[48:63], v[104:107], v[128:131], v[48:63]
	ds_read_b64_tr_b16 v[128:129], v188 offset:0x2400
	ds_read_b64_tr_b16 v[130:131], v188 offset:0x2c00
	s_waitcnt lgkmcnt(14)
	v_mfma_f32_32x32x16_bf16 v[32:47], v[104:107], v[132:135], v[32:47]
	ds_read_b64_tr_b16 v[132:133], v188 offset:0x2600
	ds_read_b64_tr_b16 v[134:135], v188 offset:0x2e00
	s_waitcnt lgkmcnt(14)
	v_mfma_f32_32x32x16_bf16 v[48:63], v[108:111], v[136:139], v[48:63]
	ds_read_b64_tr_b16 v[136:137], v188 offset:0x3400
	ds_read_b64_tr_b16 v[138:139], v188 offset:0x3c00
	s_waitcnt lgkmcnt(14)
	v_mfma_f32_32x32x16_bf16 v[32:47], v[108:111], v[140:143], v[32:47]
	ds_read_b64_tr_b16 v[144:145], v188 offset:0x3600
	ds_read_b64_tr_b16 v[146:147], v188 offset:0x3e00
	s_waitcnt lgkmcnt(14)
	v_mfma_f32_32x32x16_bf16 v[16:31], v[96:99], v[112:115], v[16:31]
	s_waitcnt lgkmcnt(12)
	v_mfma_f32_32x32x16_bf16 v[0:15], v[96:99], v[116:119], v[0:15]
	s_waitcnt lgkmcnt(10)
	v_mfma_f32_32x32x16_bf16 v[16:31], v[100:103], v[120:123], v[16:31]
	s_waitcnt lgkmcnt(8)
	v_mfma_f32_32x32x16_bf16 v[0:15], v[100:103], v[124:127], v[0:15]
	s_waitcnt lgkmcnt(6)
	v_mfma_f32_32x32x16_bf16 v[16:31], v[104:107], v[128:131], v[16:31]
	s_waitcnt lgkmcnt(4)
	v_mfma_f32_32x32x16_bf16 v[0:15], v[104:107], v[132:135], v[0:15]
	s_waitcnt lgkmcnt(2)
	v_mfma_f32_32x32x16_bf16 v[16:31], v[108:111], v[136:139], v[16:31]
	s_waitcnt lgkmcnt(0)
	v_mfma_f32_32x32x16_bf16 v[0:15], v[108:111], v[144:147], v[0:15]
	v_lshl_add_u64 v[96:97], s[92:93], 0, v[164:165]
	s_mov_b32 s0, 0x20000
	v_add_co_u32_e32 v96, vcc, s0, v96
	s_nop 1
	v_addc_co_u32_e32 v97, vcc, 0, v97, vcc
	global_load_dwordx4 v[132:135], v[96:97], off
	v_lshl_add_u64 v[96:97], s[84:85], 0, v[164:165]
	v_add_co_u32_e32 v96, vcc, 0x20000, v96
	global_load_dwordx4 v[144:147], v164, s[92:93]
	global_load_dwordx4 v[128:131], v164, s[84:85]
	v_addc_co_u32_e32 v97, vcc, 0, v97, vcc
	global_load_dwordx4 v[136:139], v[96:97], off
	global_load_dwordx4 v[140:143], v174, s[72:73]
	s_cmpk_lt_u32 s94, 0x200
	s_cbranch_scc0 .LBB0_994
	v_subrev_u32_e32 v96, s1, v203
	v_add_u32_e32 v96, 64, v96
	v_cmp_gt_i32_e64 s[64:65], 26, v96
	v_cmp_gt_i32_e64 s[66:67], 27, v96
	v_cmp_gt_i32_e64 s[62:63], 25, v96
	s_and_b64 s[64:65], s[66:67], s[64:65]
	v_cmp_gt_i32_e64 s[60:61], 24, v96
	s_and_b64 s[62:63], s[64:65], s[62:63]
	v_cmp_gt_i32_e64 s[58:59], 19, v96
	s_and_b64 s[60:61], s[62:63], s[60:61]
	v_cmp_gt_i32_e64 s[56:57], 18, v96
	s_and_b64 s[58:59], s[60:61], s[58:59]
	v_cmp_gt_i32_e64 s[54:55], 17, v96
	s_and_b64 s[56:57], s[58:59], s[56:57]
	v_cmp_gt_i32_e64 s[52:53], 16, v96
	s_and_b64 s[54:55], s[56:57], s[54:55]
	v_cmp_gt_i32_e64 s[50:51], 11, v96
	s_and_b64 s[52:53], s[54:55], s[52:53]
	v_cmp_gt_i32_e64 s[48:49], 10, v96
	s_and_b64 s[50:51], s[52:53], s[50:51]
	v_cmp_gt_i32_e64 s[46:47], 9, v96
	s_and_b64 s[48:49], s[50:51], s[48:49]
	v_cmp_gt_i32_e64 s[44:45], 8, v96
	s_and_b64 s[46:47], s[48:49], s[46:47]
	v_cmp_gt_i32_e64 s[42:43], 3, v96
	s_and_b64 s[44:45], s[46:47], s[44:45]
	v_cmp_gt_i32_e64 s[40:41], 2, v96
	s_and_b64 s[42:43], s[44:45], s[42:43]
	v_cmp_gt_i32_e64 s[38:39], 1, v96
	s_and_b64 s[40:41], s[42:43], s[40:41]
	v_cmp_gt_i32_e64 s[34:35], 0, v96
	s_and_b64 s[38:39], s[40:41], s[38:39]
	s_and_b64 s[34:35], s[38:39], s[34:35]
	v_cmp_gt_i32_e64 s[30:31], 58, v96
	v_cndmask_b32_e64 v80, v80, v198, s[34:35]
	v_cmp_gt_i32_e64 s[34:35], 59, v96
	v_cmp_gt_i32_e64 s[28:29], 57, v96
	s_and_b64 s[30:31], s[34:35], s[30:31]
	v_cmp_gt_i32_e64 s[26:27], 56, v96
	s_and_b64 s[28:29], s[30:31], s[28:29]
	v_cmp_gt_i32_e64 s[24:25], 51, v96
	s_and_b64 s[26:27], s[28:29], s[26:27]
	v_cmp_gt_i32_e64 s[22:23], 50, v96
	s_and_b64 s[24:25], s[26:27], s[24:25]
	v_cmp_gt_i32_e64 s[20:21], 49, v96
	s_and_b64 s[22:23], s[24:25], s[22:23]
	v_cmp_gt_i32_e64 s[18:19], 48, v96
	s_and_b64 s[20:21], s[22:23], s[20:21]
	v_cmp_gt_i32_e64 s[16:17], 43, v96
	s_and_b64 s[18:19], s[20:21], s[18:19]
	v_cmp_gt_i32_e64 s[14:15], 42, v96
	s_and_b64 s[16:17], s[18:19], s[16:17]
	v_cmp_gt_i32_e64 s[12:13], 41, v96
	s_and_b64 s[14:15], s[16:17], s[14:15]
	v_cmp_gt_i32_e64 s[10:11], 40, v96
	s_and_b64 s[12:13], s[14:15], s[12:13]
	v_cmp_gt_i32_e64 s[8:9], 35, v96
	s_and_b64 s[10:11], s[12:13], s[10:11]
	v_cmp_gt_i32_e64 s[6:7], 34, v96
	s_and_b64 s[8:9], s[10:11], s[8:9]
	v_cmp_gt_i32_e64 s[0:1], 33, v96
	s_and_b64 s[6:7], s[8:9], s[6:7]
	v_cmp_gt_i32_e32 vcc, 32, v96
	s_and_b64 s[0:1], s[6:7], s[0:1]
	s_and_b64 vcc, s[0:1], vcc
	v_cndmask_b32_e64 v95, v95, v198, s[66:67]
	v_cndmask_b32_e64 v94, v94, v198, s[64:65]
	v_cndmask_b32_e64 v93, v93, v198, s[62:63]
	v_cndmask_b32_e64 v92, v92, v198, s[60:61]
	v_cndmask_b32_e64 v91, v91, v198, s[58:59]
	v_cndmask_b32_e64 v90, v90, v198, s[56:57]
	v_cndmask_b32_e64 v89, v89, v198, s[54:55]
	v_cndmask_b32_e64 v88, v88, v198, s[52:53]
	v_cndmask_b32_e64 v87, v87, v198, s[50:51]
	v_cndmask_b32_e64 v86, v86, v198, s[48:49]
	v_cndmask_b32_e64 v85, v85, v198, s[46:47]
	v_cndmask_b32_e64 v84, v84, v198, s[44:45]
	v_cndmask_b32_e64 v83, v83, v198, s[42:43]
	v_cndmask_b32_e64 v82, v82, v198, s[40:41]
	v_cndmask_b32_e64 v81, v81, v198, s[38:39]
	v_cndmask_b32_e64 v79, v79, v198, s[34:35]
	v_cndmask_b32_e64 v78, v78, v198, s[30:31]
	v_cndmask_b32_e64 v77, v77, v198, s[28:29]
	v_cndmask_b32_e64 v76, v76, v198, s[26:27]
	v_cndmask_b32_e64 v75, v75, v198, s[24:25]
	v_cndmask_b32_e64 v74, v74, v198, s[22:23]
	v_cndmask_b32_e64 v73, v73, v198, s[20:21]
	v_cndmask_b32_e64 v72, v72, v198, s[18:19]
	v_cndmask_b32_e64 v71, v71, v198, s[16:17]
	v_cndmask_b32_e64 v70, v70, v198, s[14:15]
	v_cndmask_b32_e64 v69, v69, v198, s[12:13]
	v_cndmask_b32_e64 v68, v68, v198, s[10:11]
	v_cndmask_b32_e64 v67, v67, v198, s[8:9]
	v_cndmask_b32_e64 v66, v66, v198, s[6:7]
	v_cndmask_b32_e64 v65, v65, v198, s[0:1]
	v_cndmask_b32_e32 v64, v64, v198, vcc

; #define SBAR() __builtin_amdgcn_sched_barrier(0)
; #define RESC(a) do { if (__any((a) < 1.f)) { if (hi == 0) al_l[r32] = (a); asm volatile("s_waitcnt lgkmcnt(0)" ::: "memory");              \
;                      _Pragma("unroll") for (int d_ = 0; d_ < 4; ++d_) _Pragma("unroll") for (int r = 0; r < 16; ++r) o[d_][r] *= al_l[crow(r, hi)]; } } while (0)
; __device__ __forceinline__ void partialSM(f32x16& p0, f32x16& p1, float& m_reg, float& mn, float& alpha) {
;     float pmax = p0[0];
; #pragma unroll
;     for (int r = 1; r < 16; ++r) pmax = fmaxf(pmax, p0[r]);
; #pragma unroll
;     for (int r = 0; r < 16; ++r) pmax = fmaxf(pmax, p1[r]);
;     { auto rr = __builtin_amdgcn_permlane32_swap(__float_as_uint(pmax), __float_as_uint(pmax), false, false);
;       pmax = fmaxf(__uint_as_float(rr[0]), __uint_as_float(rr[1])); }
;     constexpr float C2 = 1.4426950408889634f * SCALE;
;     if (__builtin_expect(__all((pmax - m_reg) * SCALE <= THR), 1)) { mn = m_reg; alpha = 1.f; }
;     else { mn = fmaxf(m_reg, pmax); alpha = __builtin_amdgcn_exp2f((m_reg - mn) * C2); m_reg = mn; }
;     const float mnL = -mn * C2;
; #pragma unroll
;     for (int r = 0; r < 16; ++r) p0[r] = fmaf(p0[r], C2, mnL);
; #pragma unroll
;     for (int r = 0; r < 16; ++r) p1[r] = fmaf(p1[r], C2, mnL);
; #pragma unroll
;     for (int r = 0; r < 16; ++r) p0[r] = __builtin_amdgcn_exp2f(p0[r]);
; }
; __device__ __forceinline__ void finishSM(f32x16& p0, f32x16& p1, float alpha, float& l_reg, bf16x8& pa0, bf16x8& pa1, bf16x8& pa2, bf16x8& pa3) {
; #pragma unroll
;     for (int r = 0; r < 16; ++r) p1[r] = __builtin_amdgcn_exp2f(p1[r]);
;     float ps = 0;
; #pragma unroll
;     for (int r = 0; r < 16; ++r) ps += p0[r];
; #pragma unroll
;     for (int r = 0; r < 16; ++r) ps += p1[r];
;     { auto rr = __builtin_amdgcn_permlane32_swap(__float_as_uint(ps), __float_as_uint(ps), false, false);
;       ps = __uint_as_float(rr[0]) + __uint_as_float(rr[1]); }
;     l_reg = l_reg * alpha + ps;
;     PK4(p0, 0, pa0); PK4(p0, 8, pa1); PK4(p1, 0, pa2); PK4(p1, 8, pa3);
; }
; __device__ __forceinline__ void attn_block(const BlockRef& cur, const BlockRef& nxt, char* lds, Seam& S) {
;     ...
;     MASKT(pB0, pB1, NT - 1); partialSM(pB0, pB1, m_reg, mnB, alB); __syncthreads(); RESC(alB);
;     finishSM(pB0, pB1, alB, l_reg, pa0, pa1, pa2, pa3); SBAR(); pv_tile<1>(o, vb0, pa0, pa1, pa2, pa3);
.LBB0_998:
	v_cndmask_b32_e64 v96, v96, v148, s[6:7]
	v_mul_f32_e32 v96, 0xbdd53b94, v96
	v_fmamk_f32 v80, v80, 0x3dd53b94, v96
	v_fmamk_f32 v81, v81, 0x3dd53b94, v96
	v_fmamk_f32 v97, v82, 0x3dd53b94, v96
	v_exp_f32_e32 v82, v80
	v_fmamk_f32 v98, v84, 0x3dd53b94, v96
	v_exp_f32_e32 v84, v81
	v_fmamk_f32 v83, v83, 0x3dd53b94, v96
	v_exp_f32_e32 v80, v97
	v_fmamk_f32 v64, v64, 0x3dd53b94, v96
	v_exp_f32_e32 v83, v83
	v_fmamk_f32 v99, v85, 0x3dd53b94, v96
	v_fmamk_f32 v108, v94, 0x3dd53b94, v96
	v_fmamk_f32 v94, v75, 0x3dd53b94, v96
	v_exp_f32_e32 v75, v98
	v_exp_f32_e32 v97, v64
	v_add_f32_e32 v64, 0, v82
	v_fmamk_f32 v100, v86, 0x3dd53b94, v96
	v_exp_f32_e32 v81, v99
	v_add_f32_e32 v64, v84, v64
	v_fmamk_f32 v101, v87, 0x3dd53b94, v96
	v_fmamk_f32 v107, v93, 0x3dd53b94, v96
	v_fmamk_f32 v93, v74, 0x3dd53b94, v96
	v_exp_f32_e32 v74, v100
	v_add_f32_e32 v64, v80, v64
	v_fmamk_f32 v102, v88, 0x3dd53b94, v96
	v_fmamk_f32 v109, v95, 0x3dd53b94, v96
	v_fmamk_f32 v95, v76, 0x3dd53b94, v96
	v_exp_f32_e32 v76, v101
	v_add_f32_e32 v64, v83, v64
	v_fmamk_f32 v103, v89, 0x3dd53b94, v96
	v_fmamk_f32 v104, v90, 0x3dd53b94, v96
	v_fmamk_f32 v90, v71, 0x3dd53b94, v96
	v_exp_f32_e32 v71, v102
	v_add_f32_e32 v64, v75, v64
	v_fmamk_f32 v106, v92, 0x3dd53b94, v96
	v_fmamk_f32 v92, v73, 0x3dd53b94, v96
	v_exp_f32_e32 v73, v103
	v_add_f32_e32 v64, v81, v64
	v_fmamk_f32 v105, v91, 0x3dd53b94, v96
	v_fmamk_f32 v88, v69, 0x3dd53b94, v96
	v_exp_f32_e32 v69, v104
	v_add_f32_e32 v64, v74, v64
	v_fmamk_f32 v91, v72, 0x3dd53b94, v96
	v_exp_f32_e32 v72, v105
	v_add_f32_e32 v64, v76, v64
	v_fmamk_f32 v86, v67, 0x3dd53b94, v96
	v_exp_f32_e32 v67, v106
	v_add_f32_e32 v64, v71, v64
	v_fmamk_f32 v89, v70, 0x3dd53b94, v96
	v_exp_f32_e32 v70, v107
	v_add_f32_e32 v64, v73, v64
	v_fmamk_f32 v85, v66, 0x3dd53b94, v96
	v_exp_f32_e32 v66, v108
	v_add_f32_e32 v64, v69, v64
	v_fmamk_f32 v87, v68, 0x3dd53b94, v96
	v_exp_f32_e32 v68, v109
	v_add_f32_e32 v64, v72, v64
	v_fmamk_f32 v65, v65, 0x3dd53b94, v96
	v_add_f32_e32 v64, v67, v64
	v_exp_f32_e32 v98, v65
	v_add_f32_e32 v64, v70, v64
	v_exp_f32_e32 v85, v85
	v_add_f32_e32 v64, v66, v64
	v_exp_f32_e32 v86, v86
	v_add_f32_e32 v64, v68, v64
	v_exp_f32_e32 v87, v87
	v_add_f32_e32 v64, v97, v64
	v_exp_f32_e32 v88, v88
	v_add_f32_e32 v64, v98, v64
	v_exp_f32_e32 v89, v89
	v_add_f32_e32 v64, v85, v64
	v_exp_f32_e32 v90, v90
	v_add_f32_e32 v64, v86, v64
	v_exp_f32_e32 v91, v91
	v_add_f32_e32 v64, v87, v64
	v_exp_f32_e32 v92, v92
	v_add_f32_e32 v64, v88, v64
	v_exp_f32_e32 v93, v93
	v_add_f32_e32 v64, v89, v64
	v_exp_f32_e32 v94, v94
	v_add_f32_e32 v64, v90, v64
	v_fmamk_f32 v77, v77, 0x3dd53b94, v96
	v_exp_f32_e32 v95, v95
	v_add_f32_e32 v64, v91, v64
	v_fmamk_f32 v78, v78, 0x3dd53b94, v96
	v_exp_f32_e32 v99, v77
	v_add_f32_e32 v64, v92, v64
	v_fmac_f32_e32 v96, 0x3dd53b94, v79
	v_exp_f32_e32 v100, v78
	v_add_f32_e32 v64, v93, v64
	v_exp_f32_e32 v96, v96
	v_add_f32_e32 v64, v94, v64
	v_add_f32_e32 v64, v95, v64
	v_add_f32_e32 v64, v99, v64
	v_add_f32_e32 v64, v100, v64
	v_add_f32_e32 v64, v96, v64
	v_mov_b32_e32 v65, v64
	s_nop 1
	v_permlane32_swap_b32_e32 v64, v65
	v_cvt_pk_bf16_f32 v78, v82, v84
	v_cvt_pk_bf16_f32 v79, v80, v83
	v_cvt_pk_bf16_f32 v80, v75, v81
	v_cvt_pk_bf16_f32 v81, v74, v76
	v_cvt_pk_bf16_f32 v74, v71, v73
	v_cvt_pk_bf16_f32 v75, v69, v72
	v_cvt_pk_bf16_f32 v76, v67, v70
	v_cvt_pk_bf16_f32 v77, v66, v68
	v_cvt_pk_bf16_f32 v66, v97, v98
	v_cvt_pk_bf16_f32 v67, v85, v86
	v_cvt_pk_bf16_f32 v68, v87, v88
	v_cvt_pk_bf16_f32 v69, v89, v90
	v_cvt_pk_bf16_f32 v70, v91, v92
	v_cvt_pk_bf16_f32 v71, v93, v94
	v_cvt_pk_bf16_f32 v72, v95, v99
	v_cvt_pk_bf16_f32 v73, v100, v96
	s_nop 0
	v_permlane32_swap_b32_e32 v78, v80
	v_permlane32_swap_b32_e32 v79, v81
	v_permlane32_swap_b32_e32 v74, v76
	v_permlane32_swap_b32_e32 v75, v77
	v_permlane32_swap_b32_e32 v66, v68
	v_permlane32_swap_b32_e32 v67, v69
	v_permlane32_swap_b32_e32 v70, v72
	v_permlane32_swap_b32_e32 v71, v73
	ds_read_b64_tr_b16 v[82:83], v188 offset:0x4000
	ds_read_b64_tr_b16 v[84:85], v188 offset:0x4800
	ds_read_b64_tr_b16 v[86:87], v188 offset:0x4200
	ds_read_b64_tr_b16 v[88:89], v188 offset:0x4a00
	ds_read_b64_tr_b16 v[90:91], v188 offset:0x5000
	ds_read_b64_tr_b16 v[92:93], v188 offset:0x5800
	ds_read_b64_tr_b16 v[94:95], v188 offset:0x5200
	ds_read_b64_tr_b16 v[96:97], v188 offset:0x5a00
	ds_read_b64_tr_b16 v[98:99], v188 offset:0x6000
	ds_read_b64_tr_b16 v[100:101], v188 offset:0x6800
	ds_read_b64_tr_b16 v[102:103], v188 offset:0x6200
	ds_read_b64_tr_b16 v[104:105], v188 offset:0x6a00
	ds_read_b64_tr_b16 v[106:107], v188 offset:0x7000
	ds_read_b64_tr_b16 v[108:109], v188 offset:0x7800
	ds_read_b64_tr_b16 v[110:111], v188 offset:0x7200
	ds_read_b64_tr_b16 v[112:113], v188 offset:0x7a00
	s_waitcnt lgkmcnt(14)
; #define SBAR() __builtin_amdgcn_sched_barrier(0)
; #define QLOAD(R) do { _Pragma("unroll") for (int d0 = 0; d0 < 8; ++d0) S.qr[d0] = *(const bf16x8*)((R).QN + d0 * 16 + qoff); } while (0)
; #define SEAM_K0() do { VMWN(8); SWRITE_HK(0); SBAR(); } while (0)
; template <int VB>
; __device__ __forceinline__ void pv_tile(f32x16* o, int vb0, bf16x8 pa0, bf16x8 pa1, bf16x8 pa2, bf16x8 pa3) {
;     ...
;     PV_D2(0, 1); PV_D2(2, 3);
; __device__ __forceinline__ void attn_block(const BlockRef& cur, const BlockRef& nxt, char* lds, Seam& S) {
;     ...
;     SBAR(); QLOAD(nxt); SBAR();
;     SEAM_K0();
;     if (hi == 0) li_l[r32] = l_reg; asm volatile("s_waitcnt lgkmcnt(0)" ::: "memory");
	s_nop 0
	v_mfma_f32_32x32x16_bf16 v[48:63], v[78:81], v[82:85], v[48:63]
	ds_read_b64_tr_b16 v[82:83], v188 offset:0x4400
	ds_read_b64_tr_b16 v[84:85], v188 offset:0x4c00
	s_waitcnt lgkmcnt(14)
	v_mfma_f32_32x32x16_bf16 v[32:47], v[78:81], v[86:89], v[32:47]
	ds_read_b64_tr_b16 v[86:87], v188 offset:0x4600
	ds_read_b64_tr_b16 v[88:89], v188 offset:0x4e00
	s_waitcnt lgkmcnt(14)
	v_mfma_f32_32x32x16_bf16 v[48:63], v[74:77], v[90:93], v[48:63]
	ds_read_b64_tr_b16 v[90:91], v188 offset:0x5400
	ds_read_b64_tr_b16 v[92:93], v188 offset:0x5c00
	s_waitcnt lgkmcnt(14)
	v_mfma_f32_32x32x16_bf16 v[32:47], v[74:77], v[94:97], v[32:47]
	ds_read_b64_tr_b16 v[94:95], v188 offset:0x5600
	ds_read_b64_tr_b16 v[96:97], v188 offset:0x5e00
	s_waitcnt lgkmcnt(14)
	v_mfma_f32_32x32x16_bf16 v[48:63], v[66:69], v[98:101], v[48:63]
	ds_read_b64_tr_b16 v[98:99], v188 offset:0x6400
	ds_read_b64_tr_b16 v[100:101], v188 offset:0x6c00
	s_waitcnt lgkmcnt(14)
	v_mfma_f32_32x32x16_bf16 v[32:47], v[66:69], v[102:105], v[32:47]
	ds_read_b64_tr_b16 v[102:103], v188 offset:0x6600
	ds_read_b64_tr_b16 v[104:105], v188 offset:0x6e00
	s_waitcnt lgkmcnt(14)
	v_mfma_f32_32x32x16_bf16 v[48:63], v[70:73], v[106:109], v[48:63]
	ds_read_b64_tr_b16 v[106:107], v188 offset:0x7400
	ds_read_b64_tr_b16 v[108:109], v188 offset:0x7c00
	s_waitcnt lgkmcnt(14)
	v_mfma_f32_32x32x16_bf16 v[32:47], v[70:73], v[110:113], v[32:47]
	ds_read_b64_tr_b16 v[114:115], v188 offset:0x7600
	ds_read_b64_tr_b16 v[116:117], v188 offset:0x7e00
	s_waitcnt lgkmcnt(14)
	v_mfma_f32_32x32x16_bf16 v[16:31], v[78:81], v[82:85], v[16:31]
	s_waitcnt lgkmcnt(12)
	v_mfma_f32_32x32x16_bf16 v[0:15], v[78:81], v[86:89], v[0:15]
	s_waitcnt lgkmcnt(10)
	v_mfma_f32_32x32x16_bf16 v[16:31], v[74:77], v[90:93], v[16:31]
	s_waitcnt lgkmcnt(8)
	v_mfma_f32_32x32x16_bf16 v[0:15], v[74:77], v[94:97], v[0:15]
	s_waitcnt lgkmcnt(6)
	v_mfma_f32_32x32x16_bf16 v[16:31], v[66:69], v[98:101], v[16:31]
	s_waitcnt lgkmcnt(4)
	v_mfma_f32_32x32x16_bf16 v[0:15], v[66:69], v[102:105], v[0:15]
	s_waitcnt lgkmcnt(2)
	v_mfma_f32_32x32x16_bf16 v[16:31], v[70:73], v[106:109], v[16:31]
	s_waitcnt lgkmcnt(0)
	v_mfma_f32_32x32x16_bf16 v[0:15], v[70:73], v[114:117], v[0:15]
	v_lshl_or_b32 v66, v200, 12, v193
	global_load_dwordx4 v[124:127], v66, s[86:87]
	global_load_dwordx4 v[120:123], v66, s[86:87] offset:32
	global_load_dwordx4 v[116:119], v66, s[86:87] offset:64
	global_load_dwordx4 v[112:115], v66, s[86:87] offset:96
	global_load_dwordx4 v[108:111], v66, s[86:87] offset:128
	global_load_dwordx4 v[104:107], v66, s[86:87] offset:160
	global_load_dwordx4 v[100:103], v66, s[86:87] offset:192
	global_load_dwordx4 v[96:99], v66, s[86:87] offset:224
	s_waitcnt vmcnt(8)
	s_waitcnt vmcnt(10)
	ds_write_b128 v169, v[128:131]
	s_waitcnt vmcnt(9)
	ds_write_b128 v169, v[136:139] offset:12288
	s_waitcnt vmcnt(8)
	ds_write_b128 v182, v[140:143]
	s_and_saveexec_b64 s[0:1], s[2:3]
	s_cbranch_execz .LBB0_957
	v_add_f32_e32 v66, v162, v163
	v_fmac_f32_e32 v66, v202, v149
	v_add_f32_e32 v64, v64, v65
	v_fmac_f32_e32 v64, v66, v150
	ds_write_b32 v201, v64
	s_branch .LBB0_957
